# plus: GLA pre-pass gate loop: broadcast LDS reads of the low-rank rows hoisted 12 reads ahead (renamed to a private register pool, counted lgkmcnt)
# speedup vs baseline: 1.0378x; 1.0048x over previous
.LBB0_611:
	s_or_b64 exec, exec, s[62:63]
	s_lshl_b32 s0, s36, 8
	s_and_b32 s0, s0, 0x700
	s_lshl_b32 s0, s0, 1
	s_add_u32 s62, s56, s0
	s_addc_u32 s63, s57, 0
	v_mov_b32_e32 v69, v1
	v_lshl_add_u64 v[42:43], s[62:63], 0, v[68:69]
	v_add_u32_e32 v0, s38, v73
	v_mad_i64_i32 v[18:19], s[64:65], v0, s80, v[42:43]
	v_add_co_u32_e32 v22, vcc, s81, v18
	v_add_u32_e32 v0, s38, v74
	s_nop 0
	v_addc_co_u32_e32 v23, vcc, 0, v19, vcc
	v_mad_i64_i32 v[26:27], s[64:65], v0, s80, v[42:43]
	v_add_co_u32_e32 v30, vcc, s81, v26
	v_add_u32_e32 v0, s38, v75
	s_nop 0
	v_addc_co_u32_e32 v31, vcc, 0, v27, vcc
	v_mad_i64_i32 v[34:35], s[64:65], v0, s80, v[42:43]
	v_add_co_u32_e32 v38, vcc, s81, v34
	v_add_u32_e32 v0, s38, v76
	s_nop 0
	v_addc_co_u32_e32 v39, vcc, 0, v35, vcc
	v_mad_i64_i32 v[42:43], s[64:65], v0, s80, v[42:43]
	v_add_co_u32_e32 v46, vcc, s81, v42
	global_load_dwordx4 v[18:21], v[18:19], off
	s_nop 0
	global_load_dwordx4 v[22:25], v[22:23], off
	v_addc_co_u32_e32 v47, vcc, 0, v43, vcc
	global_load_dwordx4 v[26:29], v[26:27], off
	s_nop 0
	global_load_dwordx4 v[30:33], v[30:31], off
	s_nop 0
	global_load_dwordx4 v[34:37], v[34:35], off
	s_nop 0
	global_load_dwordx4 v[38:41], v[38:39], off
	s_nop 0
	global_load_dwordx4 v[42:45], v[42:43], off
	s_nop 0
	global_load_dwordx4 v[46:49], v[46:47], off
	s_waitcnt lgkmcnt(0)
	s_barrier
	ds_read_b128 v[120:123], v77
	ds_read_b128 v[124:127], v77 offset:16
	ds_read_b128 v[128:131], v77 offset:32
	ds_read_b128 v[132:135], v77 offset:48
	ds_read_b128 v[136:139], v77 offset:64
	ds_read_b128 v[140:143], v77 offset:80
	ds_read_b128 v[144:147], v77 offset:96
	ds_read_b128 v[148:151], v77 offset:112
	ds_read_b128 v[152:155], v77 offset:144
	ds_read_b128 v[156:159], v77 offset:128
	ds_read_b128 v[160:163], v77 offset:160
	ds_read_b128 v[164:167], v77 offset:176
	ds_read_b128 v[168:171], v77 offset:192
	ds_read_b128 v[172:175], v77 offset:208
	ds_read_b128 v[176:179], v77 offset:224
	ds_read_b128 v[180:183], v77 offset:240
	s_waitcnt vmcnt(24) lgkmcnt(15)
	v_mul_f32_e32 v0, v3, v121
	s_waitcnt vmcnt(22)
	v_mul_f32_e32 v69, v5, v123
	s_waitcnt vmcnt(9)
	v_fmac_f32_e32 v0, v2, v120
	v_fmac_f32_e32 v69, v4, v122
	v_add_f32_e32 v0, v0, v69
	s_waitcnt lgkmcnt(14)
	v_mul_f32_e32 v69, v7, v125
	v_mul_f32_e32 v80, v9, v127
	v_fmac_f32_e32 v69, v6, v124
	v_fmac_f32_e32 v80, v8, v126
	s_waitcnt vmcnt(8)
	v_add_f32_e32 v0, v79, v0
	v_add_f32_e32 v69, v69, v80
	v_add_f32_e32 v0, v0, v69
	s_waitcnt lgkmcnt(13)
	v_mul_f32_e32 v69, v11, v129
	v_mul_f32_e32 v80, v13, v131
	v_fmac_f32_e32 v69, v10, v128
	v_fmac_f32_e32 v80, v12, v130
	v_add_f32_e32 v69, v69, v80
	v_add_f32_e32 v0, v0, v69
	s_waitcnt lgkmcnt(12)
	v_mul_f32_e32 v69, v15, v133
	v_mul_f32_e32 v80, v17, v135
	v_fmac_f32_e32 v69, v14, v132
	v_fmac_f32_e32 v80, v16, v134
	v_add_f32_e32 v69, v69, v80
	ds_read_b128 v[120:123], v77 offset:256
	ds_read_b128 v[124:127], v77 offset:272
	v_add_f32_e32 v0, v0, v69
	v_mul_f32_e64 v69, |v0|, s82
	v_exp_f32_e32 v69, v69
	s_waitcnt lgkmcnt(13)
	v_mul_f32_e32 v81, v3, v137
	v_fmac_f32_e32 v81, v2, v136
	v_mul_f32_e32 v80, v5, v139
	v_fmac_f32_e32 v80, v4, v138
	v_add_f32_e32 v80, v81, v80
	s_waitcnt lgkmcnt(12)
	v_mul_f32_e32 v85, v7, v141
	v_add_f32_e32 v88, v79, v80
	v_fmac_f32_e32 v85, v6, v140
	v_mul_f32_e32 v84, v9, v143
	ds_read_b128 v[128:131], v77 offset:288
	v_fmac_f32_e32 v84, v8, v142
	v_add_f32_e32 v84, v85, v84
	v_add_f32_e32 v88, v88, v84
	ds_read_b128 v[132:135], v77 offset:304
	s_waitcnt lgkmcnt(13)
	v_mul_f32_e32 v81, v11, v145
	v_fmac_f32_e32 v81, v10, v144
	v_mul_f32_e32 v80, v13, v147
	v_fmac_f32_e32 v80, v12, v146
	v_add_f32_e32 v80, v81, v80
	s_waitcnt lgkmcnt(12)
	v_mul_f32_e32 v81, v15, v149
	v_mul_f32_e32 v82, v17, v151
	v_fmac_f32_e32 v81, v14, v148
	v_fmac_f32_e32 v82, v16, v150
	v_add_f32_e32 v80, v88, v80
	v_add_f32_e32 v81, v81, v82
	v_add_f32_e32 v84, v80, v81
	v_add_f32_e32 v69, 1.0, v69
	v_mul_f32_e64 v80, |v84|, s82
	v_log_f32_e32 v69, v69
	v_exp_f32_e32 v80, v80
	v_max_f32_e64 v0, -v0, 0
	ds_read_b128 v[136:139], v77 offset:320
	v_fmac_f32_e32 v0, 0x3f317218, v69
	v_add_f32_e32 v69, 1.0, v80
	ds_read_b128 v[140:143], v77 offset:336
	v_log_f32_e32 v69, v69
	v_fma_f32 v86, v0, s83, 0
	v_max_f32_e64 v0, -v84, 0
	s_waitcnt lgkmcnt(13)
	v_mul_f32_e32 v84, v7, v153
	v_fmac_f32_e32 v0, 0x3f317218, v69
	s_waitcnt lgkmcnt(12)
	v_mul_f32_e32 v69, v3, v157
	v_fmac_f32_e32 v69, v2, v156
	v_mul_f32_e32 v80, v5, v159
	v_fmac_f32_e32 v80, v4, v158
	v_add_f32_e32 v69, v69, v80
	ds_read_b128 v[144:147], v77 offset:352
	v_mul_f32_e32 v85, v9, v155
	v_fmac_f32_e32 v84, v6, v152
	v_fmac_f32_e32 v85, v8, v154
	ds_read_b128 v[148:151], v77 offset:368
	s_waitcnt lgkmcnt(13)
	v_mul_f32_e32 v81, v11, v161
	v_fmac_f32_e32 v81, v10, v160
	v_mul_f32_e32 v80, v13, v163
	v_add_f32_e32 v69, v79, v69
	v_add_f32_e32 v84, v84, v85
	v_fmac_f32_e32 v80, v12, v162
	v_add_f32_e32 v69, v69, v84
	v_add_f32_e32 v80, v81, v80
	v_add_f32_e32 v69, v69, v80
	s_waitcnt lgkmcnt(12)
	v_mul_f32_e32 v80, v15, v165
	v_mul_f32_e32 v81, v17, v167
	v_fmac_f32_e32 v80, v14, v164
	v_fmac_f32_e32 v81, v16, v166
	v_add_f32_e32 v80, v80, v81
	v_add_f32_e32 v69, v69, v80
	v_mul_f32_e64 v80, |v69|, s82
	v_exp_f32_e32 v84, v80
	ds_read_b128 v[152:155], v77 offset:384
	ds_read_b128 v[156:159], v77 offset:400
	v_max_f32_e64 v69, -v69, 0
	v_add_f32_e32 v84, 1.0, v84
	v_log_f32_e32 v84, v84
	s_waitcnt lgkmcnt(13)
	v_mul_f32_e32 v81, v3, v169
	v_fmac_f32_e32 v81, v2, v168
	v_mul_f32_e32 v80, v5, v171
	v_fmac_f32_e32 v80, v4, v170
	v_add_f32_e32 v80, v81, v80
	v_add_f32_e32 v85, v79, v80
	s_waitcnt lgkmcnt(12)
	v_mul_f32_e32 v87, v7, v173
	ds_read_b128 v[160:163], v77 offset:416
	v_fmac_f32_e32 v87, v6, v172
	v_mul_f32_e32 v88, v9, v175
	v_fmac_f32_e32 v88, v8, v174
	v_add_f32_e32 v87, v87, v88
	ds_read_b128 v[164:167], v77 offset:432
	s_waitcnt lgkmcnt(13)
	v_mul_f32_e32 v81, v11, v177
	v_fmac_f32_e32 v81, v10, v176
	v_mul_f32_e32 v80, v13, v179
	v_fmac_f32_e32 v80, v12, v178
	v_add_f32_e32 v80, v81, v80
	s_waitcnt lgkmcnt(12)
	v_mul_f32_e32 v81, v15, v181
	v_mul_f32_e32 v82, v17, v183
	v_add_f32_e32 v85, v85, v87
	v_fmac_f32_e32 v81, v14, v180
	v_fmac_f32_e32 v82, v16, v182
	v_add_f32_e32 v80, v85, v80
	v_add_f32_e32 v81, v81, v82
	v_add_f32_e32 v85, v80, v81
	v_mul_f32_e64 v80, |v85|, s82
	v_exp_f32_e32 v87, v80
	ds_read_b128 v[168:171], v77 offset:448
	ds_read_b128 v[172:175], v77 offset:464
	v_fmac_f32_e32 v69, 0x3f317218, v84
	v_add_f32_e32 v84, 1.0, v87
	v_log_f32_e32 v84, v84
	s_waitcnt lgkmcnt(13)
	v_mul_f32_e32 v81, v3, v121
	v_fmac_f32_e32 v81, v2, v120
	v_mul_f32_e32 v80, v5, v123
	v_fmac_f32_e32 v80, v4, v122
	v_add_f32_e32 v80, v81, v80
	s_waitcnt lgkmcnt(12)
	v_mul_f32_e32 v89, v7, v125
	v_add_f32_e32 v87, v79, v80
	v_fmac_f32_e32 v89, v6, v124
	v_mul_f32_e32 v88, v9, v127
	ds_read_b128 v[176:179], v77 offset:480
	v_fmac_f32_e32 v88, v8, v126
	v_add_f32_e32 v88, v89, v88
	v_add_f32_e32 v87, v87, v88
	ds_read_b128 v[180:183], v77 offset:496
	s_waitcnt lgkmcnt(13)
	v_mul_f32_e32 v81, v11, v129
	v_fmac_f32_e32 v81, v10, v128
	v_mul_f32_e32 v80, v13, v131
	v_fmac_f32_e32 v80, v12, v130
	v_add_f32_e32 v80, v81, v80
	s_waitcnt lgkmcnt(12)
	v_mul_f32_e32 v81, v15, v133
	v_mul_f32_e32 v82, v17, v135
	v_fmac_f32_e32 v81, v14, v132
	v_fmac_f32_e32 v82, v16, v134
	v_add_f32_e32 v80, v87, v80
	v_add_f32_e32 v81, v81, v82
	v_add_f32_e32 v87, v80, v81
	v_mul_f32_e64 v80, |v87|, s82
	v_exp_f32_e32 v88, v80
	ds_read_b128 v[120:123], v77 offset:512
	v_max_f32_e64 v85, -v85, 0
	v_fmac_f32_e32 v85, 0x3f317218, v84
	v_add_f32_e32 v84, 1.0, v88
	ds_read_b128 v[124:127], v77 offset:528
	s_waitcnt lgkmcnt(13)
	v_mul_f32_e32 v81, v3, v137
	v_fmac_f32_e32 v81, v2, v136
	v_mul_f32_e32 v80, v5, v139
	v_fmac_f32_e32 v80, v4, v138
	v_add_f32_e32 v80, v81, v80
	s_waitcnt lgkmcnt(12)
	v_mul_f32_e32 v89, v7, v141
	v_add_f32_e32 v92, v79, v80
	v_fmac_f32_e32 v89, v6, v140
	v_mul_f32_e32 v88, v9, v143
	ds_read_b128 v[128:131], v77 offset:544
	v_fmac_f32_e32 v88, v8, v142
	v_add_f32_e32 v88, v89, v88
	v_add_f32_e32 v92, v92, v88
	ds_read_b128 v[132:135], v77 offset:560
	s_waitcnt lgkmcnt(13)
	v_mul_f32_e32 v81, v11, v145
	v_fmac_f32_e32 v81, v10, v144
	v_mul_f32_e32 v80, v13, v147
	v_fmac_f32_e32 v80, v12, v146
	v_add_f32_e32 v80, v81, v80
	s_waitcnt lgkmcnt(12)
	v_mul_f32_e32 v81, v15, v149
	v_mul_f32_e32 v82, v17, v151
	v_fmac_f32_e32 v81, v14, v148
	v_fmac_f32_e32 v82, v16, v150
	v_add_f32_e32 v80, v92, v80
	v_add_f32_e32 v81, v81, v82
	v_add_f32_e32 v88, v80, v81
	v_mul_f32_e64 v80, |v88|, s82
	v_exp_f32_e32 v80, v80
	v_log_f32_e32 v84, v84
	v_fmamk_f32 v0, v0, 0xbd800000, v86
	v_fmamk_f32 v69, v69, 0xbd800000, v0
	v_add_f32_e32 v80, 1.0, v80
	v_max_f32_e64 v87, -v87, 0
	v_log_f32_e32 v89, v80
	v_fmamk_f32 v81, v85, 0xbd800000, v69
	v_fmac_f32_e32 v87, 0x3f317218, v84
	ds_read_b128 v[136:139], v77 offset:576
	v_fmamk_f32 v80, v87, 0xbd800000, v81
	v_max_f32_e64 v87, -v88, 0
	v_fmac_f32_e32 v87, 0x3f317218, v89
	ds_read_b128 v[140:143], v77 offset:592
	s_waitcnt lgkmcnt(13)
	v_mul_f32_e32 v83, v3, v153
	v_fmac_f32_e32 v83, v2, v152
	v_mul_f32_e32 v82, v5, v155
	v_fmac_f32_e32 v82, v4, v154
	v_add_f32_e32 v82, v83, v82
	s_waitcnt lgkmcnt(12)
	v_mul_f32_e32 v89, v7, v157
	v_add_f32_e32 v92, v79, v82
	v_fmac_f32_e32 v89, v6, v156
	v_mul_f32_e32 v88, v9, v159
	ds_read_b128 v[144:147], v77 offset:608
	v_fmac_f32_e32 v88, v8, v158
	v_add_f32_e32 v88, v89, v88
	v_add_f32_e32 v92, v92, v88
	ds_read_b128 v[148:151], v77 offset:624
	s_waitcnt lgkmcnt(13)
	v_mul_f32_e32 v83, v11, v161
	v_fmac_f32_e32 v83, v10, v160
	v_mul_f32_e32 v82, v13, v163
	v_fmac_f32_e32 v82, v12, v162
	v_add_f32_e32 v82, v83, v82
	s_waitcnt lgkmcnt(12)
	v_mul_f32_e32 v83, v15, v165
	v_mul_f32_e32 v84, v17, v167
	v_fmac_f32_e32 v83, v14, v164
	v_fmac_f32_e32 v84, v16, v166
	ds_read_b128 v[152:155], v77 offset:640
	v_add_f32_e32 v82, v92, v82
	v_add_f32_e32 v83, v83, v84
	ds_read_b128 v[156:159], v77 offset:656
	v_add_f32_e32 v83, v82, v83
	v_mul_f32_e64 v82, |v83|, s82
	v_exp_f32_e32 v84, v82
	v_fmamk_f32 v82, v87, 0xbd800000, v80
	s_waitcnt lgkmcnt(13)
	v_mul_f32_e32 v85, v3, v169
	v_mul_f32_e32 v87, v5, v171
	v_fmac_f32_e32 v85, v2, v168
	v_fmac_f32_e32 v87, v4, v170
	ds_read_b128 v[160:163], v77 offset:672
	v_add_f32_e32 v85, v85, v87
	s_waitcnt lgkmcnt(13)
	v_mul_f32_e32 v87, v7, v173
	v_fmac_f32_e32 v87, v6, v172
	v_mul_f32_e32 v92, v9, v175
	v_fmac_f32_e32 v92, v8, v174
	v_add_f32_e32 v85, v79, v85
	v_add_f32_e32 v87, v87, v92
	ds_read_b128 v[164:167], v77 offset:688
	v_add_f32_e32 v85, v85, v87
	s_waitcnt lgkmcnt(13)
	v_mul_f32_e32 v87, v11, v177
	v_fmac_f32_e32 v87, v10, v176
	v_mul_f32_e32 v88, v13, v179
	v_fmac_f32_e32 v88, v12, v178
	v_add_f32_e32 v87, v87, v88
	v_add_f32_e32 v85, v85, v87
	s_waitcnt lgkmcnt(12)
	v_mul_f32_e32 v87, v15, v181
	v_mul_f32_e32 v88, v17, v183
	v_fmac_f32_e32 v87, v14, v180
	v_fmac_f32_e32 v88, v16, v182
	v_add_f32_e32 v87, v87, v88
	v_add_f32_e32 v85, v85, v87
	v_add_f32_e32 v84, 1.0, v84
	v_mul_f32_e64 v87, |v85|, s82
	ds_read_b128 v[168:171], v77 offset:704
	ds_read_b128 v[172:175], v77 offset:720
	v_log_f32_e32 v84, v84
	v_exp_f32_e32 v87, v87
	v_max_f32_e64 v83, -v83, 0
	v_max_f32_e64 v85, -v85, 0
	v_fmac_f32_e32 v83, 0x3f317218, v84
	v_add_f32_e32 v84, 1.0, v87
	s_waitcnt lgkmcnt(13)
	v_mul_f32_e32 v87, v3, v121
	v_fmac_f32_e32 v87, v2, v120
	v_mul_f32_e32 v88, v5, v123
	v_fmac_f32_e32 v88, v4, v122
	v_add_f32_e32 v87, v87, v88
	s_waitcnt lgkmcnt(12)
	v_mul_f32_e32 v93, v7, v125
	ds_read_b128 v[176:179], v77 offset:736
	v_fmac_f32_e32 v93, v6, v124
	v_mul_f32_e32 v92, v9, v127
	v_fmac_f32_e32 v92, v8, v126
	v_add_f32_e32 v87, v79, v87
	v_add_f32_e32 v92, v93, v92
	v_add_f32_e32 v87, v87, v92
	ds_read_b128 v[180:183], v77 offset:752
	s_waitcnt lgkmcnt(13)
	v_mul_f32_e32 v89, v11, v129
	v_fmac_f32_e32 v89, v10, v128
	v_mul_f32_e32 v88, v13, v131
	v_fmac_f32_e32 v88, v12, v130
	v_add_f32_e32 v88, v89, v88
	v_add_f32_e32 v87, v87, v88
	s_waitcnt lgkmcnt(12)
	v_mul_f32_e32 v88, v15, v133
	v_mul_f32_e32 v89, v17, v135
	v_fmac_f32_e32 v88, v14, v132
	v_fmac_f32_e32 v89, v16, v134
	v_add_f32_e32 v88, v88, v89
	v_add_f32_e32 v87, v87, v88
	v_mul_f32_e64 v88, |v87|, s82
	v_log_f32_e32 v84, v84
	v_exp_f32_e32 v92, v88
	ds_read_b128 v[120:123], v77 offset:768
	v_max_f32_e64 v87, -v87, 0
	v_fmac_f32_e32 v85, 0x3f317218, v84
	v_add_f32_e32 v84, 1.0, v92
	ds_read_b128 v[124:127], v77 offset:784
	s_waitcnt lgkmcnt(13)
	v_mul_f32_e32 v89, v3, v137
	v_fmac_f32_e32 v89, v2, v136
	v_mul_f32_e32 v88, v5, v139
	v_fmac_f32_e32 v88, v4, v138
	v_add_f32_e32 v88, v89, v88
	s_waitcnt lgkmcnt(12)
	v_mul_f32_e32 v93, v7, v141
	v_add_f32_e32 v96, v79, v88
	v_fmac_f32_e32 v93, v6, v140
	v_mul_f32_e32 v92, v9, v143
	ds_read_b128 v[128:131], v77 offset:800
	v_fmac_f32_e32 v92, v8, v142
	v_add_f32_e32 v92, v93, v92
	v_add_f32_e32 v96, v96, v92
	ds_read_b128 v[132:135], v77 offset:816
	s_waitcnt lgkmcnt(13)
	v_mul_f32_e32 v89, v11, v145
	v_fmac_f32_e32 v89, v10, v144
	v_mul_f32_e32 v88, v13, v147
	v_fmac_f32_e32 v88, v12, v146
	v_add_f32_e32 v88, v89, v88
	s_waitcnt lgkmcnt(12)
	v_mul_f32_e32 v89, v15, v149
	v_mul_f32_e32 v90, v17, v151
	v_fmac_f32_e32 v89, v14, v148
	v_fmac_f32_e32 v90, v16, v150
	v_add_f32_e32 v88, v96, v88
	v_add_f32_e32 v89, v89, v90
	v_add_f32_e32 v92, v88, v89
	v_mul_f32_e64 v88, |v92|, s82
	v_log_f32_e32 v84, v84
	v_exp_f32_e32 v88, v88
	v_fmamk_f32 v83, v83, 0xbd800000, v82
	v_fmamk_f32 v85, v85, 0xbd800000, v83
	v_fmac_f32_e32 v87, 0x3f317218, v84
	v_add_f32_e32 v84, 1.0, v88
	v_log_f32_e32 v93, v84
	ds_read_b128 v[136:139], v77 offset:832
	v_fmamk_f32 v84, v87, 0xbd800000, v85
	v_max_f32_e64 v87, -v92, 0
	v_fmac_f32_e32 v87, 0x3f317218, v93
	ds_read_b128 v[140:143], v77 offset:848
	s_waitcnt lgkmcnt(13)
	v_mul_f32_e32 v89, v3, v153
	v_fmac_f32_e32 v89, v2, v152
	v_mul_f32_e32 v88, v5, v155
	v_fmac_f32_e32 v88, v4, v154
	v_add_f32_e32 v88, v89, v88
	s_waitcnt lgkmcnt(12)
	v_mul_f32_e32 v93, v7, v157
	v_add_f32_e32 v96, v79, v88
	v_fmac_f32_e32 v93, v6, v156
	v_mul_f32_e32 v92, v9, v159
	ds_read_b128 v[144:147], v77 offset:864
	v_fmac_f32_e32 v92, v8, v158
	v_add_f32_e32 v92, v93, v92
	v_add_f32_e32 v96, v96, v92
	ds_read_b128 v[148:151], v77 offset:880
	s_waitcnt lgkmcnt(13)
	v_mul_f32_e32 v89, v11, v161
	v_fmac_f32_e32 v89, v10, v160
	v_mul_f32_e32 v88, v13, v163
	v_fmac_f32_e32 v88, v12, v162
	v_add_f32_e32 v88, v89, v88
	s_waitcnt lgkmcnt(12)
	v_mul_f32_e32 v89, v15, v165
	v_mul_f32_e32 v90, v17, v167
	v_fmac_f32_e32 v89, v14, v164
	v_fmac_f32_e32 v90, v16, v166
	v_add_f32_e32 v88, v96, v88
	v_add_f32_e32 v89, v89, v90
	v_add_f32_e32 v92, v88, v89
	v_mul_f32_e64 v88, |v92|, s82
	v_exp_f32_e32 v93, v88
	ds_read_b128 v[152:155], v77 offset:896
	v_max_f32_e64 v96, -v92, 0
	v_fmamk_f32 v87, v87, 0xbd800000, v84
	v_add_f32_e32 v92, 1.0, v93
	v_log_f32_e32 v97, v92
	ds_read_b128 v[156:159], v77 offset:912
	s_waitcnt lgkmcnt(13)
	v_mul_f32_e32 v89, v3, v169
	v_fmac_f32_e32 v89, v2, v168
	v_mul_f32_e32 v88, v5, v171
	v_fmac_f32_e32 v88, v4, v170
	v_add_f32_e32 v88, v89, v88
	s_waitcnt lgkmcnt(12)
	v_mul_f32_e32 v93, v7, v173
	v_add_f32_e32 v98, v79, v88
	v_fmac_f32_e32 v93, v6, v172
	v_mul_f32_e32 v92, v9, v175
	ds_read_b128 v[160:163], v77 offset:928
	v_fmac_f32_e32 v92, v8, v174
	v_add_f32_e32 v92, v93, v92
	v_add_f32_e32 v98, v98, v92
	ds_read_b128 v[164:167], v77 offset:944
	s_waitcnt lgkmcnt(13)
	v_mul_f32_e32 v89, v11, v177
	v_fmac_f32_e32 v89, v10, v176
	v_mul_f32_e32 v88, v13, v179
	v_fmac_f32_e32 v88, v12, v178
	v_add_f32_e32 v88, v89, v88
	s_waitcnt lgkmcnt(12)
	v_mul_f32_e32 v89, v15, v181
	v_mul_f32_e32 v90, v17, v183
	v_fmac_f32_e32 v89, v14, v180
	v_fmac_f32_e32 v90, v16, v182
	v_add_f32_e32 v88, v98, v88
	v_add_f32_e32 v89, v89, v90
	v_add_f32_e32 v89, v88, v89
	v_mul_f32_e64 v88, |v89|, s82
	v_exp_f32_e32 v94, v88
	ds_read_b128 v[168:171], v77 offset:960
	v_fmac_f32_e32 v96, 0x3f317218, v97
	v_fmamk_f32 v88, v96, 0xbd800000, v87
	v_add_f32_e32 v94, 1.0, v94
	v_log_f32_e32 v98, v94
	ds_read_b128 v[172:175], v77 offset:976
	s_waitcnt lgkmcnt(13)
	v_mul_f32_e32 v91, v3, v121
	v_fmac_f32_e32 v91, v2, v120
	v_mul_f32_e32 v90, v5, v123
	v_fmac_f32_e32 v90, v4, v122
	v_add_f32_e32 v90, v91, v90
	s_waitcnt lgkmcnt(12)
	v_mul_f32_e32 v95, v7, v125
	v_add_f32_e32 v99, v79, v90
	v_fmac_f32_e32 v95, v6, v124
	v_mul_f32_e32 v94, v9, v127
	ds_read_b128 v[176:179], v77 offset:992
	v_fmac_f32_e32 v94, v8, v126
	v_add_f32_e32 v94, v95, v94
	v_add_f32_e32 v99, v99, v94
	ds_read_b128 v[180:183], v77 offset:1008
	s_waitcnt lgkmcnt(13)
	v_mul_f32_e32 v91, v11, v129
	v_fmac_f32_e32 v91, v10, v128
	v_mul_f32_e32 v90, v13, v131
	v_fmac_f32_e32 v90, v12, v130
	v_add_f32_e32 v90, v91, v90
	s_waitcnt lgkmcnt(12)
	v_mul_f32_e32 v91, v15, v133
	v_mul_f32_e32 v92, v17, v135
	v_fmac_f32_e32 v91, v14, v132
	v_fmac_f32_e32 v92, v16, v134
	v_add_f32_e32 v90, v99, v90
	v_add_f32_e32 v91, v91, v92
	v_add_f32_e32 v99, v90, v91
	v_mul_f32_e64 v90, |v99|, s82
	v_exp_f32_e32 v94, v90
	ds_read_b128 v[120:123], v77 offset:1024
	v_max_f32_e64 v89, -v89, 0
	v_fmac_f32_e32 v89, 0x3f317218, v98
	v_add_f32_e32 v94, 1.0, v94
	v_log_f32_e32 v98, v94
	ds_read_b128 v[124:127], v77 offset:1040
	s_waitcnt lgkmcnt(13)
	v_mul_f32_e32 v91, v3, v137
	v_fmac_f32_e32 v91, v2, v136
	v_mul_f32_e32 v90, v5, v139
	v_fmac_f32_e32 v90, v4, v138
	v_add_f32_e32 v90, v91, v90
	s_waitcnt lgkmcnt(12)
	v_mul_f32_e32 v95, v7, v141
	v_add_f32_e32 v100, v79, v90
	v_fmac_f32_e32 v95, v6, v140
	v_mul_f32_e32 v94, v9, v143
	ds_read_b128 v[128:131], v77 offset:1056
	v_fmac_f32_e32 v94, v8, v142
	v_add_f32_e32 v94, v95, v94
	v_add_f32_e32 v100, v100, v94
	ds_read_b128 v[132:135], v77 offset:1072
	s_waitcnt lgkmcnt(13)
	v_mul_f32_e32 v91, v11, v145
	v_fmac_f32_e32 v91, v10, v144
	v_mul_f32_e32 v90, v13, v147
	v_fmac_f32_e32 v90, v12, v146
	v_add_f32_e32 v90, v91, v90
	s_waitcnt lgkmcnt(12)
	v_mul_f32_e32 v91, v15, v149
	v_mul_f32_e32 v92, v17, v151
	v_fmac_f32_e32 v91, v14, v148
	v_fmac_f32_e32 v92, v16, v150
	v_add_f32_e32 v90, v100, v90
	v_add_f32_e32 v91, v91, v92
	v_add_f32_e32 v91, v90, v91
	v_mul_f32_e64 v90, |v91|, s82
	v_exp_f32_e32 v92, v90
	v_fmamk_f32 v90, v89, 0xbd800000, v88
	v_max_f32_e64 v89, -v99, 0
	v_max_f32_e64 v91, -v91, 0
	v_add_f32_e32 v92, 1.0, v92
	v_log_f32_e32 v96, v92
	ds_read_b128 v[136:139], v77 offset:1088
	v_fmac_f32_e32 v89, 0x3f317218, v98
	v_fmamk_f32 v89, v89, 0xbd800000, v90
	v_fmac_f32_e32 v91, 0x3f317218, v96
	ds_read_b128 v[140:143], v77 offset:1104
	s_waitcnt lgkmcnt(13)
	v_mul_f32_e32 v93, v3, v153
	v_fmac_f32_e32 v93, v2, v152
	v_mul_f32_e32 v92, v5, v155
	v_fmac_f32_e32 v92, v4, v154
	v_add_f32_e32 v92, v93, v92
	s_waitcnt lgkmcnt(12)
	v_mul_f32_e32 v97, v7, v157
	v_add_f32_e32 v100, v79, v92
	v_fmac_f32_e32 v97, v6, v156
	v_mul_f32_e32 v96, v9, v159
	ds_read_b128 v[144:147], v77 offset:1120
	v_fmac_f32_e32 v96, v8, v158
	v_add_f32_e32 v96, v97, v96
	v_add_f32_e32 v100, v100, v96
	ds_read_b128 v[148:151], v77 offset:1136
	s_waitcnt lgkmcnt(13)
	v_mul_f32_e32 v93, v11, v161
	v_fmac_f32_e32 v93, v10, v160
	v_mul_f32_e32 v92, v13, v163
	v_fmac_f32_e32 v92, v12, v162
	v_add_f32_e32 v92, v93, v92
	s_waitcnt lgkmcnt(12)
	v_mul_f32_e32 v93, v15, v165
	v_mul_f32_e32 v94, v17, v167
	v_fmac_f32_e32 v93, v14, v164
	v_fmac_f32_e32 v94, v16, v166
	v_add_f32_e32 v92, v100, v92
	v_add_f32_e32 v93, v93, v94
	v_add_f32_e32 v96, v92, v93
	v_mul_f32_e64 v92, |v96|, s82
	v_exp_f32_e32 v97, v92
	ds_read_b128 v[152:155], v77 offset:1152
	v_max_f32_e64 v100, -v96, 0
	v_fmamk_f32 v91, v91, 0xbd800000, v89
	v_add_f32_e32 v96, 1.0, v97
	v_log_f32_e32 v101, v96
	ds_read_b128 v[156:159], v77 offset:1168
	s_waitcnt lgkmcnt(13)
	v_mul_f32_e32 v93, v3, v169
	v_fmac_f32_e32 v93, v2, v168
	v_mul_f32_e32 v92, v5, v171
	v_fmac_f32_e32 v92, v4, v170
	v_add_f32_e32 v92, v93, v92
	s_waitcnt lgkmcnt(12)
	v_mul_f32_e32 v97, v7, v173
	v_add_f32_e32 v102, v79, v92
	v_fmac_f32_e32 v97, v6, v172
	v_mul_f32_e32 v96, v9, v175
	ds_read_b128 v[160:163], v77 offset:1184
	v_fmac_f32_e32 v96, v8, v174
	v_add_f32_e32 v96, v97, v96
	v_add_f32_e32 v102, v102, v96
	ds_read_b128 v[164:167], v77 offset:1200
	s_waitcnt lgkmcnt(13)
	v_mul_f32_e32 v93, v11, v177
	v_fmac_f32_e32 v93, v10, v176
	v_mul_f32_e32 v92, v13, v179
	v_fmac_f32_e32 v92, v12, v178
	v_add_f32_e32 v92, v93, v92
	s_waitcnt lgkmcnt(12)
	v_mul_f32_e32 v93, v15, v181
	v_mul_f32_e32 v94, v17, v183
	v_fmac_f32_e32 v93, v14, v180
	v_fmac_f32_e32 v94, v16, v182
	v_add_f32_e32 v92, v102, v92
	v_add_f32_e32 v93, v93, v94
	v_add_f32_e32 v93, v92, v93
	v_mul_f32_e64 v92, |v93|, s82
	v_exp_f32_e32 v98, v92
	ds_read_b128 v[168:171], v77 offset:1216
	v_fmac_f32_e32 v100, 0x3f317218, v101
	v_fmamk_f32 v92, v100, 0xbd800000, v91
	v_add_f32_e32 v98, 1.0, v98
	v_log_f32_e32 v102, v98
	ds_read_b128 v[172:175], v77 offset:1232
	s_waitcnt lgkmcnt(13)
	v_mul_f32_e32 v95, v3, v121
	v_fmac_f32_e32 v95, v2, v120
	v_mul_f32_e32 v94, v5, v123
	v_fmac_f32_e32 v94, v4, v122
	v_add_f32_e32 v94, v95, v94
	s_waitcnt lgkmcnt(12)
	v_mul_f32_e32 v99, v7, v125
	v_add_f32_e32 v103, v79, v94
	v_fmac_f32_e32 v99, v6, v124
	v_mul_f32_e32 v98, v9, v127
	ds_read_b128 v[176:179], v77 offset:1248
	v_fmac_f32_e32 v98, v8, v126
	v_add_f32_e32 v98, v99, v98
	v_add_f32_e32 v103, v103, v98
	ds_read_b128 v[180:183], v77 offset:1264
	s_waitcnt lgkmcnt(13)
	v_mul_f32_e32 v95, v11, v129
	v_fmac_f32_e32 v95, v10, v128
	v_mul_f32_e32 v94, v13, v131
	v_fmac_f32_e32 v94, v12, v130
	v_add_f32_e32 v94, v95, v94
	s_waitcnt lgkmcnt(12)
	v_mul_f32_e32 v95, v15, v133
	v_mul_f32_e32 v96, v17, v135
	v_fmac_f32_e32 v95, v14, v132
	v_fmac_f32_e32 v96, v16, v134
	v_add_f32_e32 v94, v103, v94
	v_add_f32_e32 v95, v95, v96
	v_add_f32_e32 v103, v94, v95
	v_mul_f32_e64 v94, |v103|, s82
	v_exp_f32_e32 v98, v94
	ds_read_b128 v[120:123], v77 offset:1280
	v_max_f32_e64 v93, -v93, 0
	v_fmac_f32_e32 v93, 0x3f317218, v102
	v_add_f32_e32 v98, 1.0, v98
	v_log_f32_e32 v102, v98
	ds_read_b128 v[124:127], v77 offset:1296
	s_waitcnt lgkmcnt(13)
	v_mul_f32_e32 v95, v3, v137
	v_fmac_f32_e32 v95, v2, v136
	v_mul_f32_e32 v94, v5, v139
	v_fmac_f32_e32 v94, v4, v138
	v_add_f32_e32 v94, v95, v94
	s_waitcnt lgkmcnt(12)
	v_mul_f32_e32 v99, v7, v141
	v_add_f32_e32 v104, v79, v94
	v_fmac_f32_e32 v99, v6, v140
	v_mul_f32_e32 v98, v9, v143
	ds_read_b128 v[128:131], v77 offset:1312
	v_fmac_f32_e32 v98, v8, v142
	v_add_f32_e32 v98, v99, v98
	v_add_f32_e32 v104, v104, v98
	ds_read_b128 v[132:135], v77 offset:1328
	s_waitcnt lgkmcnt(13)
	v_mul_f32_e32 v95, v11, v145
	v_fmac_f32_e32 v95, v10, v144
	v_mul_f32_e32 v94, v13, v147
	v_fmac_f32_e32 v94, v12, v146
	v_add_f32_e32 v94, v95, v94
	s_waitcnt lgkmcnt(12)
	v_mul_f32_e32 v95, v15, v149
	v_mul_f32_e32 v96, v17, v151
	v_fmac_f32_e32 v95, v14, v148
	v_fmac_f32_e32 v96, v16, v150
	v_add_f32_e32 v94, v104, v94
	v_add_f32_e32 v95, v95, v96
	v_add_f32_e32 v95, v94, v95
	v_mul_f32_e64 v94, |v95|, s82
	v_exp_f32_e32 v96, v94
	v_fmamk_f32 v94, v93, 0xbd800000, v92
	v_max_f32_e64 v93, -v103, 0
	v_max_f32_e64 v95, -v95, 0
	v_add_f32_e32 v96, 1.0, v96
	v_log_f32_e32 v100, v96
	ds_read_b128 v[136:139], v77 offset:1344
	v_fmac_f32_e32 v93, 0x3f317218, v102
	v_fmamk_f32 v93, v93, 0xbd800000, v94
	v_fmac_f32_e32 v95, 0x3f317218, v100
	ds_read_b128 v[140:143], v77 offset:1360
	s_waitcnt lgkmcnt(13)
	v_mul_f32_e32 v97, v3, v153
	v_fmac_f32_e32 v97, v2, v152
	v_mul_f32_e32 v96, v5, v155
	v_fmac_f32_e32 v96, v4, v154
	v_add_f32_e32 v96, v97, v96
	s_waitcnt lgkmcnt(12)
	v_mul_f32_e32 v101, v7, v157
	v_add_f32_e32 v104, v79, v96
	v_fmac_f32_e32 v101, v6, v156
	v_mul_f32_e32 v100, v9, v159
	ds_read_b128 v[144:147], v77 offset:1376
	v_fmac_f32_e32 v100, v8, v158
	v_add_f32_e32 v100, v101, v100
	v_add_f32_e32 v104, v104, v100
	ds_read_b128 v[148:151], v77 offset:1392
	s_waitcnt lgkmcnt(13)
	v_mul_f32_e32 v97, v11, v161
	v_fmac_f32_e32 v97, v10, v160
	v_mul_f32_e32 v96, v13, v163
	v_fmac_f32_e32 v96, v12, v162
	v_add_f32_e32 v96, v97, v96
	s_waitcnt lgkmcnt(12)
	v_mul_f32_e32 v97, v15, v165
	v_mul_f32_e32 v98, v17, v167
	v_fmac_f32_e32 v97, v14, v164
	v_fmac_f32_e32 v98, v16, v166
	v_add_f32_e32 v96, v104, v96
	v_add_f32_e32 v97, v97, v98
	v_add_f32_e32 v100, v96, v97
	v_mul_f32_e64 v96, |v100|, s82
	v_exp_f32_e32 v101, v96
	ds_read_b128 v[152:155], v77 offset:1408
	v_max_f32_e64 v104, -v100, 0
	v_fmamk_f32 v95, v95, 0xbd800000, v93
	v_add_f32_e32 v100, 1.0, v101
	v_log_f32_e32 v105, v100
	ds_read_b128 v[156:159], v77 offset:1424
	s_waitcnt lgkmcnt(13)
	v_mul_f32_e32 v97, v3, v169
	v_fmac_f32_e32 v97, v2, v168
	v_mul_f32_e32 v96, v5, v171
	v_fmac_f32_e32 v96, v4, v170
	v_add_f32_e32 v96, v97, v96
	s_waitcnt lgkmcnt(12)
	v_mul_f32_e32 v101, v7, v173
	v_add_f32_e32 v106, v79, v96
	v_fmac_f32_e32 v101, v6, v172
	v_mul_f32_e32 v100, v9, v175
	ds_read_b128 v[160:163], v77 offset:1440
	v_fmac_f32_e32 v100, v8, v174
	v_add_f32_e32 v100, v101, v100
	v_add_f32_e32 v106, v106, v100
	ds_read_b128 v[164:167], v77 offset:1456
	s_waitcnt lgkmcnt(13)
	v_mul_f32_e32 v97, v11, v177
	v_fmac_f32_e32 v97, v10, v176
	v_mul_f32_e32 v96, v13, v179
	v_fmac_f32_e32 v96, v12, v178
	v_add_f32_e32 v96, v97, v96
	s_waitcnt lgkmcnt(12)
	v_mul_f32_e32 v97, v15, v181
	v_mul_f32_e32 v98, v17, v183
	v_fmac_f32_e32 v97, v14, v180
	v_fmac_f32_e32 v98, v16, v182
	v_add_f32_e32 v96, v106, v96
	v_add_f32_e32 v97, v97, v98
	v_add_f32_e32 v97, v96, v97
	v_mul_f32_e64 v96, |v97|, s82
	v_exp_f32_e32 v102, v96
	ds_read_b128 v[168:171], v77 offset:1472
	v_fmac_f32_e32 v104, 0x3f317218, v105
	v_fmamk_f32 v96, v104, 0xbd800000, v95
	v_add_f32_e32 v102, 1.0, v102
	v_log_f32_e32 v106, v102
	ds_read_b128 v[172:175], v77 offset:1488
	s_waitcnt lgkmcnt(13)
	v_mul_f32_e32 v99, v3, v121
	v_fmac_f32_e32 v99, v2, v120
	v_mul_f32_e32 v98, v5, v123
	v_fmac_f32_e32 v98, v4, v122
	v_add_f32_e32 v98, v99, v98
	s_waitcnt lgkmcnt(12)
	v_mul_f32_e32 v103, v7, v125
	v_add_f32_e32 v107, v79, v98
	v_fmac_f32_e32 v103, v6, v124
	v_mul_f32_e32 v102, v9, v127
	ds_read_b128 v[176:179], v77 offset:1504
	v_fmac_f32_e32 v102, v8, v126
	v_add_f32_e32 v102, v103, v102
	v_add_f32_e32 v107, v107, v102
	ds_read_b128 v[180:183], v77 offset:1520
	s_waitcnt lgkmcnt(13)
	v_mul_f32_e32 v99, v11, v129
	v_fmac_f32_e32 v99, v10, v128
	v_mul_f32_e32 v98, v13, v131
	v_fmac_f32_e32 v98, v12, v130
	v_add_f32_e32 v98, v99, v98
	s_waitcnt lgkmcnt(12)
	v_mul_f32_e32 v99, v15, v133
	v_mul_f32_e32 v100, v17, v135
	v_fmac_f32_e32 v99, v14, v132
	v_fmac_f32_e32 v100, v16, v134
	v_add_f32_e32 v98, v107, v98
	v_add_f32_e32 v99, v99, v100
	v_add_f32_e32 v107, v98, v99
	v_mul_f32_e64 v98, |v107|, s82
	v_exp_f32_e32 v102, v98
	ds_read_b128 v[120:123], v77 offset:1536
	v_max_f32_e64 v97, -v97, 0
	v_fmac_f32_e32 v97, 0x3f317218, v106
	v_add_f32_e32 v102, 1.0, v102
	v_log_f32_e32 v106, v102
	ds_read_b128 v[124:127], v77 offset:1552
	s_waitcnt lgkmcnt(13)
	v_mul_f32_e32 v99, v3, v137
	v_fmac_f32_e32 v99, v2, v136
	v_mul_f32_e32 v98, v5, v139
	v_fmac_f32_e32 v98, v4, v138
	v_add_f32_e32 v98, v99, v98
	s_waitcnt lgkmcnt(12)
	v_mul_f32_e32 v103, v7, v141
	v_add_f32_e32 v108, v79, v98
	v_fmac_f32_e32 v103, v6, v140
	v_mul_f32_e32 v102, v9, v143
	ds_read_b128 v[128:131], v77 offset:1568
	v_fmac_f32_e32 v102, v8, v142
	v_add_f32_e32 v102, v103, v102
	v_add_f32_e32 v108, v108, v102
	ds_read_b128 v[132:135], v77 offset:1584
	s_waitcnt lgkmcnt(13)
	v_mul_f32_e32 v99, v11, v145
	v_fmac_f32_e32 v99, v10, v144
	v_mul_f32_e32 v98, v13, v147
	v_fmac_f32_e32 v98, v12, v146
	v_add_f32_e32 v98, v99, v98
	s_waitcnt lgkmcnt(12)
	v_mul_f32_e32 v99, v15, v149
	v_mul_f32_e32 v100, v17, v151
	v_fmac_f32_e32 v99, v14, v148
	v_fmac_f32_e32 v100, v16, v150
	v_add_f32_e32 v98, v108, v98
	v_add_f32_e32 v99, v99, v100
	v_add_f32_e32 v99, v98, v99
	v_mul_f32_e64 v98, |v99|, s82
	v_exp_f32_e32 v100, v98
	v_fmamk_f32 v98, v97, 0xbd800000, v96
	v_max_f32_e64 v97, -v107, 0
	v_max_f32_e64 v99, -v99, 0
	v_add_f32_e32 v100, 1.0, v100
	v_log_f32_e32 v104, v100
	ds_read_b128 v[136:139], v77 offset:1600
	v_fmac_f32_e32 v97, 0x3f317218, v106
	v_fmamk_f32 v97, v97, 0xbd800000, v98
	v_fmac_f32_e32 v99, 0x3f317218, v104
	ds_read_b128 v[140:143], v77 offset:1616
	s_waitcnt lgkmcnt(13)
	v_mul_f32_e32 v101, v3, v153
	v_fmac_f32_e32 v101, v2, v152
	v_mul_f32_e32 v100, v5, v155
	v_fmac_f32_e32 v100, v4, v154
	v_add_f32_e32 v100, v101, v100
	s_waitcnt lgkmcnt(12)
	v_mul_f32_e32 v105, v7, v157
	v_add_f32_e32 v108, v79, v100
	v_fmac_f32_e32 v105, v6, v156
	v_mul_f32_e32 v104, v9, v159
	ds_read_b128 v[144:147], v77 offset:1632
	v_fmac_f32_e32 v104, v8, v158
	v_add_f32_e32 v104, v105, v104
	v_add_f32_e32 v108, v108, v104
	ds_read_b128 v[148:151], v77 offset:1648
	s_waitcnt lgkmcnt(13)
	v_mul_f32_e32 v101, v11, v161
	v_fmac_f32_e32 v101, v10, v160
	v_mul_f32_e32 v100, v13, v163
	v_fmac_f32_e32 v100, v12, v162
	v_add_f32_e32 v100, v101, v100
	s_waitcnt lgkmcnt(12)
	v_mul_f32_e32 v101, v15, v165
	v_mul_f32_e32 v102, v17, v167
	v_fmac_f32_e32 v101, v14, v164
	v_fmac_f32_e32 v102, v16, v166
	v_add_f32_e32 v100, v108, v100
	v_add_f32_e32 v101, v101, v102
	v_add_f32_e32 v104, v100, v101
	v_mul_f32_e64 v100, |v104|, s82
	v_exp_f32_e32 v105, v100
	ds_read_b128 v[152:155], v77 offset:1664
	v_max_f32_e64 v108, -v104, 0
	v_fmamk_f32 v99, v99, 0xbd800000, v97
	v_add_f32_e32 v104, 1.0, v105
	v_log_f32_e32 v109, v104
	ds_read_b128 v[156:159], v77 offset:1680
	s_waitcnt lgkmcnt(13)
	v_mul_f32_e32 v101, v3, v169
	v_fmac_f32_e32 v101, v2, v168
	v_mul_f32_e32 v100, v5, v171
	v_fmac_f32_e32 v100, v4, v170
	v_add_f32_e32 v100, v101, v100
	s_waitcnt lgkmcnt(12)
	v_mul_f32_e32 v105, v7, v173
	v_add_f32_e32 v110, v79, v100
	v_fmac_f32_e32 v105, v6, v172
	v_mul_f32_e32 v104, v9, v175
	ds_read_b128 v[160:163], v77 offset:1696
	v_fmac_f32_e32 v104, v8, v174
	v_add_f32_e32 v104, v105, v104
	v_add_f32_e32 v110, v110, v104
	ds_read_b128 v[164:167], v77 offset:1712
	s_waitcnt lgkmcnt(13)
	v_mul_f32_e32 v101, v11, v177
	v_fmac_f32_e32 v101, v10, v176
	v_mul_f32_e32 v100, v13, v179
	v_fmac_f32_e32 v100, v12, v178
	v_add_f32_e32 v100, v101, v100
	s_waitcnt lgkmcnt(12)
	v_mul_f32_e32 v101, v15, v181
	v_mul_f32_e32 v102, v17, v183
	v_fmac_f32_e32 v101, v14, v180
	v_fmac_f32_e32 v102, v16, v182
	v_add_f32_e32 v100, v110, v100
	v_add_f32_e32 v101, v101, v102
	v_add_f32_e32 v101, v100, v101
	v_mul_f32_e64 v100, |v101|, s82
	v_exp_f32_e32 v106, v100
	ds_read_b128 v[168:171], v77 offset:1728
	v_fmac_f32_e32 v108, 0x3f317218, v109
	v_fmamk_f32 v100, v108, 0xbd800000, v99
	v_add_f32_e32 v106, 1.0, v106
	v_log_f32_e32 v110, v106
	ds_read_b128 v[172:175], v77 offset:1744
	s_waitcnt lgkmcnt(13)
	v_mul_f32_e32 v103, v3, v121
	v_fmac_f32_e32 v103, v2, v120
	v_mul_f32_e32 v102, v5, v123
	v_fmac_f32_e32 v102, v4, v122
	v_add_f32_e32 v102, v103, v102
	s_waitcnt lgkmcnt(12)
	v_mul_f32_e32 v107, v7, v125
	v_add_f32_e32 v111, v79, v102
	v_fmac_f32_e32 v107, v6, v124
	v_mul_f32_e32 v106, v9, v127
	ds_read_b128 v[176:179], v77 offset:1760
	v_fmac_f32_e32 v106, v8, v126
	v_add_f32_e32 v106, v107, v106
	v_add_f32_e32 v111, v111, v106
	ds_read_b128 v[180:183], v77 offset:1776
	s_waitcnt lgkmcnt(13)
	v_mul_f32_e32 v103, v11, v129
	v_fmac_f32_e32 v103, v10, v128
	v_mul_f32_e32 v102, v13, v131
	v_fmac_f32_e32 v102, v12, v130
	v_add_f32_e32 v102, v103, v102
	s_waitcnt lgkmcnt(12)
	v_mul_f32_e32 v103, v15, v133
	v_mul_f32_e32 v104, v17, v135
	v_fmac_f32_e32 v103, v14, v132
	v_fmac_f32_e32 v104, v16, v134
	v_add_f32_e32 v102, v111, v102
	v_add_f32_e32 v103, v103, v104
	v_add_f32_e32 v111, v102, v103
	v_mul_f32_e64 v102, |v111|, s82
	v_exp_f32_e32 v106, v102
	ds_read_b128 v[120:123], v77 offset:1792
	v_max_f32_e64 v101, -v101, 0
	v_fmac_f32_e32 v101, 0x3f317218, v110
	v_add_f32_e32 v106, 1.0, v106
	v_log_f32_e32 v110, v106
	ds_read_b128 v[124:127], v77 offset:1808
	s_waitcnt lgkmcnt(13)
	v_mul_f32_e32 v103, v3, v137
	v_fmac_f32_e32 v103, v2, v136
	v_mul_f32_e32 v102, v5, v139
	v_fmac_f32_e32 v102, v4, v138
	v_add_f32_e32 v102, v103, v102
	s_waitcnt lgkmcnt(12)
	v_mul_f32_e32 v107, v7, v141
	v_add_f32_e32 v112, v79, v102
	v_fmac_f32_e32 v107, v6, v140
	v_mul_f32_e32 v106, v9, v143
	ds_read_b128 v[128:131], v77 offset:1824
	v_fmac_f32_e32 v106, v8, v142
	v_add_f32_e32 v106, v107, v106
	v_add_f32_e32 v112, v112, v106
	ds_read_b128 v[132:135], v77 offset:1840
	s_waitcnt lgkmcnt(13)
	v_mul_f32_e32 v103, v11, v145
	v_fmac_f32_e32 v103, v10, v144
	v_mul_f32_e32 v102, v13, v147
	v_fmac_f32_e32 v102, v12, v146
	v_add_f32_e32 v102, v103, v102
	s_waitcnt lgkmcnt(12)
	v_mul_f32_e32 v103, v15, v149
	v_mul_f32_e32 v104, v17, v151
	v_fmac_f32_e32 v103, v14, v148
	v_fmac_f32_e32 v104, v16, v150
	v_add_f32_e32 v102, v112, v102
	v_add_f32_e32 v103, v103, v104
	v_add_f32_e32 v103, v102, v103
	v_mul_f32_e64 v102, |v103|, s82
	v_exp_f32_e32 v104, v102
	v_fmamk_f32 v102, v101, 0xbd800000, v100
	v_max_f32_e64 v101, -v111, 0
	v_max_f32_e64 v103, -v103, 0
	v_add_f32_e32 v104, 1.0, v104
	v_log_f32_e32 v108, v104
	ds_read_b128 v[136:139], v77 offset:1856
	v_fmac_f32_e32 v101, 0x3f317218, v110
	v_fmamk_f32 v101, v101, 0xbd800000, v102
	v_fmac_f32_e32 v103, 0x3f317218, v108
	ds_read_b128 v[140:143], v77 offset:1872
	s_waitcnt lgkmcnt(13)
	v_mul_f32_e32 v105, v3, v153
	v_fmac_f32_e32 v105, v2, v152
	v_mul_f32_e32 v104, v5, v155
	v_fmac_f32_e32 v104, v4, v154
	v_add_f32_e32 v104, v105, v104
	s_waitcnt lgkmcnt(12)
	v_mul_f32_e32 v109, v7, v157
	v_add_f32_e32 v112, v79, v104
	v_fmac_f32_e32 v109, v6, v156
	v_mul_f32_e32 v108, v9, v159
	ds_read_b128 v[144:147], v77 offset:1888
	v_fmac_f32_e32 v108, v8, v158
	v_add_f32_e32 v108, v109, v108
	v_add_f32_e32 v112, v112, v108
	ds_read_b128 v[148:151], v77 offset:1904
	s_waitcnt lgkmcnt(13)
	v_mul_f32_e32 v105, v11, v161
	v_fmac_f32_e32 v105, v10, v160
	v_mul_f32_e32 v104, v13, v163
	v_fmac_f32_e32 v104, v12, v162
	v_add_f32_e32 v104, v105, v104
	s_waitcnt lgkmcnt(12)
	v_mul_f32_e32 v105, v15, v165
	v_mul_f32_e32 v106, v17, v167
	v_fmac_f32_e32 v105, v14, v164
	v_fmac_f32_e32 v106, v16, v166
	v_add_f32_e32 v104, v112, v104
	v_add_f32_e32 v105, v105, v106
	v_add_f32_e32 v108, v104, v105
	v_mul_f32_e64 v104, |v108|, s82
	v_exp_f32_e32 v109, v104
	ds_read_b128 v[152:155], v77 offset:1920
	v_max_f32_e64 v112, -v108, 0
	v_fmamk_f32 v103, v103, 0xbd800000, v101
	v_add_f32_e32 v108, 1.0, v109
	v_log_f32_e32 v113, v108
	ds_read_b128 v[156:159], v77 offset:1936
	s_waitcnt lgkmcnt(13)
	v_mul_f32_e32 v105, v3, v169
	v_fmac_f32_e32 v105, v2, v168
	v_mul_f32_e32 v104, v5, v171
	v_fmac_f32_e32 v104, v4, v170
	v_add_f32_e32 v104, v105, v104
	s_waitcnt lgkmcnt(12)
	v_mul_f32_e32 v109, v7, v173
	v_add_f32_e32 v114, v79, v104
	v_fmac_f32_e32 v109, v6, v172
	v_mul_f32_e32 v108, v9, v175
	ds_read_b128 v[160:163], v77 offset:1952
	v_fmac_f32_e32 v108, v8, v174
	v_add_f32_e32 v108, v109, v108
	v_add_f32_e32 v114, v114, v108
	ds_read_b128 v[164:167], v77 offset:1968
	s_waitcnt lgkmcnt(13)
	v_mul_f32_e32 v105, v11, v177
	v_fmac_f32_e32 v105, v10, v176
	v_mul_f32_e32 v104, v13, v179
	v_fmac_f32_e32 v104, v12, v178
	v_add_f32_e32 v104, v105, v104
	s_waitcnt lgkmcnt(12)
	v_mul_f32_e32 v105, v15, v181
	v_mul_f32_e32 v106, v17, v183
	v_fmac_f32_e32 v105, v14, v180
	v_fmac_f32_e32 v106, v16, v182
	v_add_f32_e32 v104, v114, v104
	v_add_f32_e32 v105, v105, v106
	v_add_f32_e32 v105, v104, v105
	v_mul_f32_e64 v104, |v105|, s82
	v_exp_f32_e32 v110, v104
	ds_read_b128 v[168:171], v77 offset:1984
	v_fmac_f32_e32 v112, 0x3f317218, v113
	v_fmamk_f32 v104, v112, 0xbd800000, v103
	v_add_f32_e32 v110, 1.0, v110
	v_log_f32_e32 v114, v110
	ds_read_b128 v[172:175], v77 offset:2000
	s_waitcnt lgkmcnt(13)
	v_mul_f32_e32 v107, v3, v121
	v_fmac_f32_e32 v107, v2, v120
	v_mul_f32_e32 v106, v5, v123
	v_fmac_f32_e32 v106, v4, v122
	v_add_f32_e32 v106, v107, v106
	s_waitcnt lgkmcnt(12)
	v_mul_f32_e32 v111, v7, v125
	v_add_f32_e32 v115, v79, v106
	v_fmac_f32_e32 v111, v6, v124
	v_mul_f32_e32 v110, v9, v127
	ds_read_b128 v[176:179], v77 offset:2016
	v_fmac_f32_e32 v110, v8, v126
	v_add_f32_e32 v110, v111, v110
	v_add_f32_e32 v115, v115, v110
	ds_read_b128 v[180:183], v77 offset:2032
	s_waitcnt lgkmcnt(13)
	v_mul_f32_e32 v107, v11, v129
	v_fmac_f32_e32 v107, v10, v128
	v_mul_f32_e32 v106, v13, v131
	v_fmac_f32_e32 v106, v12, v130
	v_add_f32_e32 v106, v107, v106
	s_waitcnt lgkmcnt(12)
	v_mul_f32_e32 v107, v15, v133
	v_mul_f32_e32 v108, v17, v135
	v_fmac_f32_e32 v107, v14, v132
	v_fmac_f32_e32 v108, v16, v134
	v_add_f32_e32 v106, v115, v106
	v_add_f32_e32 v107, v107, v108
	v_add_f32_e32 v115, v106, v107
	v_mul_f32_e64 v106, |v115|, s82
	v_exp_f32_e32 v110, v106
	v_max_f32_e64 v105, -v105, 0
	v_fmac_f32_e32 v105, 0x3f317218, v114
	v_add_f32_e32 v110, 1.0, v110
	v_log_f32_e32 v114, v110
	s_waitcnt lgkmcnt(11)
	v_mul_f32_e32 v107, v3, v137
	v_fmac_f32_e32 v107, v2, v136
	v_mul_f32_e32 v106, v5, v139
	v_fmac_f32_e32 v106, v4, v138
	v_add_f32_e32 v106, v107, v106
	s_waitcnt lgkmcnt(10)
	v_mul_f32_e32 v111, v7, v141
	v_add_f32_e32 v116, v79, v106
	v_fmac_f32_e32 v111, v6, v140
	v_mul_f32_e32 v110, v9, v143
	v_fmac_f32_e32 v110, v8, v142
	v_add_f32_e32 v110, v111, v110
	v_add_f32_e32 v116, v116, v110
	s_waitcnt lgkmcnt(9)
	v_mul_f32_e32 v107, v11, v145
	v_fmac_f32_e32 v107, v10, v144
	v_mul_f32_e32 v106, v13, v147
	v_fmac_f32_e32 v106, v12, v146
	v_add_f32_e32 v106, v107, v106
	s_waitcnt lgkmcnt(8)
	v_mul_f32_e32 v107, v15, v149
	v_mul_f32_e32 v108, v17, v151
	v_fmac_f32_e32 v107, v14, v148
	v_fmac_f32_e32 v108, v16, v150
	v_add_f32_e32 v106, v116, v106
	v_add_f32_e32 v107, v107, v108
	v_add_f32_e32 v112, v106, v107
	v_mul_f32_e64 v106, |v112|, s82
	v_exp_f32_e32 v106, v106
	v_fmamk_f32 v107, v105, 0xbd800000, v104
	v_max_f32_e64 v105, -v115, 0
	v_add_f32_e32 v106, 1.0, v106
	v_log_f32_e32 v113, v106
	v_fmac_f32_e32 v105, 0x3f317218, v114
	v_fmamk_f32 v106, v105, 0xbd800000, v107
	v_max_f32_e64 v105, -v112, 0
	v_fmac_f32_e32 v105, 0x3f317218, v113
	s_waitcnt lgkmcnt(7)
	v_mul_f32_e32 v109, v3, v153
	v_fmac_f32_e32 v109, v2, v152
	v_mul_f32_e32 v108, v5, v155
	v_fmac_f32_e32 v108, v4, v154
	v_add_f32_e32 v108, v109, v108
	v_add_f32_e32 v116, v79, v108
	s_waitcnt lgkmcnt(6)
	v_mul_f32_e32 v113, v7, v157
	v_fmac_f32_e32 v113, v6, v156
	v_mul_f32_e32 v112, v9, v159
	v_fmac_f32_e32 v112, v8, v158
	v_add_f32_e32 v112, v113, v112
	v_add_f32_e32 v116, v116, v112
	s_waitcnt lgkmcnt(5)
	v_mul_f32_e32 v109, v11, v161
	v_fmac_f32_e32 v109, v10, v160
	v_mul_f32_e32 v108, v13, v163
	v_fmac_f32_e32 v108, v12, v162
	v_add_f32_e32 v108, v109, v108
	v_add_f32_e32 v116, v116, v108
	s_waitcnt lgkmcnt(4)
	v_mul_f32_e32 v108, v15, v165
	v_mul_f32_e32 v109, v17, v167
	v_fmac_f32_e32 v108, v14, v164
	v_fmac_f32_e32 v109, v16, v166
	v_add_f32_e32 v112, v108, v109
	v_add_f32_e32 v116, v116, v112
	v_mul_f32_e64 v112, |v116|, s82
	v_exp_f32_e32 v117, v112
	s_waitcnt lgkmcnt(3)
	v_mul_f32_e32 v109, v3, v169
	v_fmac_f32_e32 v109, v2, v168
	v_mul_f32_e32 v108, v5, v171
	v_fmac_f32_e32 v108, v4, v170
	v_add_f32_e32 v108, v109, v108
	s_waitcnt lgkmcnt(2)
	v_mul_f32_e32 v113, v7, v173
	v_add_f32_e32 v118, v79, v108
	v_fmac_f32_e32 v113, v6, v172
	v_mul_f32_e32 v112, v9, v175
	v_fmac_f32_e32 v112, v8, v174
	v_add_f32_e32 v112, v113, v112
	v_add_f32_e32 v118, v118, v112
	s_waitcnt lgkmcnt(1)
	v_mul_f32_e32 v109, v11, v177
	v_fmac_f32_e32 v109, v10, v176
	v_mul_f32_e32 v108, v13, v179
	v_fmac_f32_e32 v108, v12, v178
	v_add_f32_e32 v108, v109, v108
	s_waitcnt lgkmcnt(0)
	v_mul_f32_e32 v109, v15, v181
	v_mul_f32_e32 v110, v17, v183
	v_fmac_f32_e32 v109, v14, v180
	v_fmac_f32_e32 v110, v16, v182
	v_add_f32_e32 v108, v118, v108
	v_add_f32_e32 v109, v109, v110
	v_add_f32_e32 v108, v108, v109
	v_mul_f32_e64 v109, |v108|, s82
	v_exp_f32_e32 v109, v109
	v_add_f32_e32 v110, 1.0, v117
	v_log_f32_e32 v110, v110
	v_max_f32_e64 v111, -v116, 0
	v_add_f32_e32 v109, 1.0, v109
	v_log_f32_e32 v112, v109
	v_fmamk_f32 v105, v105, 0xbd800000, v106
	v_fmac_f32_e32 v111, 0x3f317218, v110
	v_max_f32_e64 v108, -v108, 0
	v_fmamk_f32 v109, v111, 0xbd800000, v105
	v_fmac_f32_e32 v108, 0x3f317218, v112
	v_fmamk_f32 v108, v108, 0xbd800000, v109
	ds_write_b32 v78, v108
	s_waitcnt vmcnt(7)
	ds_write_b128 v54, v[18:21]
	s_waitcnt vmcnt(6)
	ds_write_b128 v54, v[22:25] offset:33792
	s_waitcnt vmcnt(5)
	ds_write_b128 v56, v[26:29]
	s_waitcnt vmcnt(4)
	ds_write_b128 v56, v[30:33] offset:33792
	s_waitcnt vmcnt(3)
	ds_write_b128 v58, v[34:37]
	s_waitcnt vmcnt(2)
	ds_write_b128 v58, v[38:41] offset:33792
	s_waitcnt vmcnt(1)
	ds_write_b128 v60, v[42:45]
	s_waitcnt vmcnt(0)
	ds_write_b128 v60, v[46:49] offset:33792
	s_waitcnt lgkmcnt(0)
	s_barrier
	ds_read_b32 v18, v57
	ds_read_u16 v20, v59 offset:33792
	ds_read_u16 v21, v59 offset:34320
	ds_read_u16 v22, v59 offset:34848
	ds_read_u16 v23, v59 offset:35376
	ds_read_u16 v24, v59 offset:35904
	ds_read_u16 v25, v59 offset:36432
	ds_read_u16 v26, v59 offset:36960
	s_waitcnt lgkmcnt(7)
	v_cndmask_b32_e64 v19, v18, 0, s[4:5]
	v_add_f32_e32 v27, v86, v19
	v_mul_f32_e32 v36, 0x3fb8aa3b, v27
	v_mul_f32_e32 v27, 0xbfb8aa3b, v27
	v_exp_f32_e32 v27, v27
	s_waitcnt lgkmcnt(6)
	v_lshlrev_b32_e32 v20, 16, v20
	v_add_f32_e32 v0, v0, v19
	s_waitcnt lgkmcnt(5)
	v_lshlrev_b32_e32 v21, 16, v21
	v_mul_f32_e32 v20, v27, v20
	v_mul_f32_e32 v27, 0x3fb8aa3b, v0
	v_mul_f32_e32 v0, 0xbfb8aa3b, v0
	v_exp_f32_e32 v0, v0
	ds_read_u16 v28, v59
	ds_read_u16 v29, v59 offset:528
	ds_read_u16 v30, v59 offset:1056
	ds_read_u16 v31, v59 offset:1584
	ds_read_u16 v32, v59 offset:2112
	ds_read_u16 v33, v59 offset:2640
	ds_read_u16 v34, v59 offset:3168
	ds_read_u16 v35, v59 offset:50160
	v_exp_f32_e32 v27, v27
	v_cvt_pk_bf16_f32 v20, v20, s0
	v_mul_f32_e32 v0, v0, v21
	v_cvt_pk_bf16_f32 v0, v0, s0
	ds_write_b16 v59, v0 offset:34320
	v_add_f32_e32 v0, v69, v19
	s_waitcnt lgkmcnt(13)
	v_lshlrev_b32_e32 v21, 16, v22
	v_mul_f32_e32 v22, 0x3fb8aa3b, v0
	v_mul_f32_e32 v0, 0xbfb8aa3b, v0
	v_exp_f32_e32 v0, v0
	ds_write_b16 v59, v20 offset:33792
	s_waitcnt lgkmcnt(8)
	v_lshlrev_b32_e32 v20, 16, v29
	v_mul_f32_e32 v20, 0x3d800000, v20
	v_mul_f32_e32 v20, v27, v20
	v_exp_f32_e32 v22, v22
	v_cvt_pk_bf16_f32 v20, v20, s0
	v_mul_f32_e32 v0, v0, v21
	ds_write_b16 v59, v20 offset:528
	s_waitcnt lgkmcnt(8)
	v_lshlrev_b32_e32 v20, 16, v30
	v_cvt_pk_bf16_f32 v0, v0, s0
	v_mul_f32_e32 v20, 0x3d800000, v20
	ds_write_b16 v59, v0 offset:34848
	v_add_f32_e32 v0, v81, v19
	v_mul_f32_e32 v20, v22, v20
	v_mul_f32_e32 v22, 0x3fb8aa3b, v0
	v_mul_f32_e32 v0, 0xbfb8aa3b, v0
	v_exp_f32_e32 v0, v0
	v_lshlrev_b32_e32 v21, 16, v23
	v_exp_f32_e32 v22, v22
	v_cvt_pk_bf16_f32 v20, v20, s0
	v_mul_f32_e32 v0, v0, v21
	ds_write_b16 v59, v20 offset:1056
	s_waitcnt lgkmcnt(9)
	v_lshlrev_b32_e32 v20, 16, v31
	v_cvt_pk_bf16_f32 v0, v0, s0
	v_mul_f32_e32 v20, 0x3d800000, v20
	ds_write_b16 v59, v0 offset:35376
	v_add_f32_e32 v0, v80, v19
	v_mul_f32_e32 v20, v22, v20
	v_mul_f32_e32 v22, 0x3fb8aa3b, v0
	v_mul_f32_e32 v0, 0xbfb8aa3b, v0
	v_exp_f32_e32 v0, v0
	v_lshlrev_b32_e32 v21, 16, v24
	v_exp_f32_e32 v22, v22
	v_cvt_pk_bf16_f32 v20, v20, s0
	v_mul_f32_e32 v0, v0, v21
	ds_write_b16 v59, v20 offset:1584
	s_waitcnt lgkmcnt(10)
	v_lshlrev_b32_e32 v20, 16, v32
	v_cvt_pk_bf16_f32 v0, v0, s0
	v_mul_f32_e32 v20, 0x3d800000, v20
	ds_write_b16 v59, v0 offset:35904
	v_add_f32_e32 v0, v82, v19
	v_mul_f32_e32 v20, v22, v20
	v_mul_f32_e32 v22, 0x3fb8aa3b, v0
	v_mul_f32_e32 v0, 0xbfb8aa3b, v0
	v_exp_f32_e32 v0, v0
	v_lshlrev_b32_e32 v21, 16, v25
	v_exp_f32_e32 v22, v22
	v_cvt_pk_bf16_f32 v20, v20, s0
	v_mul_f32_e32 v0, v0, v21
	ds_write_b16 v59, v20 offset:2112
	s_waitcnt lgkmcnt(11)
	v_lshlrev_b32_e32 v20, 16, v33
	v_cvt_pk_bf16_f32 v0, v0, s0
	v_mul_f32_e32 v20, 0x3d800000, v20
	ds_write_b16 v59, v0 offset:36432
	v_add_f32_e32 v0, v83, v19
	v_mul_f32_e32 v20, v22, v20
	v_mul_f32_e32 v22, 0x3fb8aa3b, v0
	v_mul_f32_e32 v0, 0xbfb8aa3b, v0
	v_exp_f32_e32 v0, v0
	v_exp_f32_e32 v36, v36
	v_lshlrev_b32_e32 v21, 16, v26
	v_exp_f32_e32 v22, v22
	v_cvt_pk_bf16_f32 v20, v20, s0
	v_mul_f32_e32 v0, v0, v21
	v_lshlrev_b32_e32 v28, 16, v28
	ds_write_b16 v59, v20 offset:2640
	s_waitcnt lgkmcnt(12)
	v_lshlrev_b32_e32 v20, 16, v34
	v_cvt_pk_bf16_f32 v0, v0, s0
	v_mul_f32_e32 v28, 0x3d800000, v28
	v_mul_f32_e32 v20, 0x3d800000, v20
	ds_write_b16 v59, v0 offset:36960
	v_add_f32_e32 v0, v85, v19
	v_mul_f32_e32 v28, v36, v28
	v_mul_f32_e32 v20, v22, v20
	v_mul_f32_e32 v37, 0x3fb8aa3b, v0
	v_mul_f32_e32 v0, 0xbfb8aa3b, v0
	v_cvt_pk_bf16_f32 v28, v28, s0
	v_cvt_pk_bf16_f32 v20, v20, s0
	v_exp_f32_e32 v0, v0
	ds_write_b16 v59, v28
	ds_write_b16 v59, v20 offset:3168
	ds_read_u16 v20, v59 offset:3696
	ds_read_u16 v21, v59 offset:4224
	ds_read_u16 v22, v59 offset:4752
	ds_read_u16 v23, v59 offset:5280
	ds_read_u16 v24, v59 offset:5808
	ds_read_u16 v25, v59 offset:6336
	ds_read_u16 v26, v59 offset:6864
	ds_read_u16 v27, v59 offset:7392
	ds_read_u16 v28, v59 offset:37488
	ds_read_u16 v29, v59 offset:38016
	ds_read_u16 v30, v59 offset:38544
	ds_read_u16 v31, v59 offset:39072
	ds_read_u16 v32, v59 offset:39600
	ds_read_u16 v33, v59 offset:40128
	ds_read_u16 v34, v59 offset:40656
	ds_read_u16 v36, v59 offset:41184
	s_waitcnt lgkmcnt(7)
	v_lshlrev_b32_e32 v28, 16, v28
	v_mul_f32_e32 v0, v0, v28
	v_exp_f32_e32 v37, v37
	v_cvt_pk_bf16_f32 v0, v0, s0
	ds_write_b16 v59, v0 offset:37488
	v_add_f32_e32 v0, v84, v19
	v_lshlrev_b32_e32 v20, 16, v20
	v_mul_f32_e32 v28, 0x3fb8aa3b, v0
	v_mul_f32_e32 v0, 0xbfb8aa3b, v0
	v_mul_f32_e32 v20, 0x3d800000, v20
	v_exp_f32_e32 v0, v0
	v_mul_f32_e32 v20, v37, v20
	v_exp_f32_e32 v28, v28
	v_cvt_pk_bf16_f32 v20, v20, s0
	ds_write_b16 v59, v20 offset:3696
	v_lshlrev_b32_e32 v20, 16, v21
	s_waitcnt lgkmcnt(8)
	v_lshlrev_b32_e32 v21, 16, v29
	v_mul_f32_e32 v20, 0x3d800000, v20
	v_mul_f32_e32 v0, v0, v21
	v_mul_f32_e32 v20, v28, v20
	v_cvt_pk_bf16_f32 v0, v0, s0
	v_cvt_pk_bf16_f32 v20, v20, s0
	ds_write_b16 v59, v0 offset:38016
	v_add_f32_e32 v0, v87, v19
	ds_write_b16 v59, v20 offset:4224
	v_lshlrev_b32_e32 v20, 16, v22
	v_mul_f32_e32 v22, 0x3fb8aa3b, v0
	v_mul_f32_e32 v0, 0xbfb8aa3b, v0
	v_exp_f32_e32 v0, v0
	s_waitcnt lgkmcnt(9)
	v_lshlrev_b32_e32 v21, 16, v30
	v_exp_f32_e32 v22, v22
	v_mul_f32_e32 v20, 0x3d800000, v20
	v_mul_f32_e32 v0, v0, v21
	v_cvt_pk_bf16_f32 v0, v0, s0
	ds_write_b16 v59, v0 offset:38544
	v_add_f32_e32 v0, v88, v19
	v_mul_f32_e32 v20, v22, v20
	v_mul_f32_e32 v22, 0x3fb8aa3b, v0
	v_mul_f32_e32 v0, 0xbfb8aa3b, v0
	v_exp_f32_e32 v0, v0
	s_waitcnt lgkmcnt(9)
	v_lshlrev_b32_e32 v21, 16, v31
	v_exp_f32_e32 v22, v22
	v_cvt_pk_bf16_f32 v20, v20, s0
	v_mul_f32_e32 v0, v0, v21
	ds_write_b16 v59, v20 offset:4752
	v_lshlrev_b32_e32 v20, 16, v23
	v_cvt_pk_bf16_f32 v0, v0, s0
	v_mul_f32_e32 v20, 0x3d800000, v20
	ds_write_b16 v59, v0 offset:39072
	v_add_f32_e32 v0, v90, v19
	v_mul_f32_e32 v20, v22, v20
	v_mul_f32_e32 v22, 0x3fb8aa3b, v0
	v_mul_f32_e32 v0, 0xbfb8aa3b, v0
	v_exp_f32_e32 v0, v0
	s_waitcnt lgkmcnt(10)
	v_lshlrev_b32_e32 v21, 16, v32
	v_exp_f32_e32 v22, v22
	v_cvt_pk_bf16_f32 v20, v20, s0
	v_mul_f32_e32 v0, v0, v21
	ds_write_b16 v59, v20 offset:5280
	v_lshlrev_b32_e32 v20, 16, v24
	v_cvt_pk_bf16_f32 v0, v0, s0
	v_mul_f32_e32 v20, 0x3d800000, v20
	ds_write_b16 v59, v0 offset:39600
	v_add_f32_e32 v0, v89, v19
	v_mul_f32_e32 v20, v22, v20
	v_mul_f32_e32 v22, 0x3fb8aa3b, v0
	v_mul_f32_e32 v0, 0xbfb8aa3b, v0
	v_exp_f32_e32 v0, v0
	s_waitcnt lgkmcnt(11)
	v_lshlrev_b32_e32 v21, 16, v33
	v_exp_f32_e32 v22, v22
	v_cvt_pk_bf16_f32 v20, v20, s0
	v_mul_f32_e32 v0, v0, v21
	ds_write_b16 v59, v20 offset:5808
	v_lshlrev_b32_e32 v20, 16, v25
	v_cvt_pk_bf16_f32 v0, v0, s0
	v_mul_f32_e32 v20, 0x3d800000, v20
	ds_write_b16 v59, v0 offset:40128
	v_add_f32_e32 v0, v91, v19
	v_mul_f32_e32 v20, v22, v20
	v_mul_f32_e32 v22, 0x3fb8aa3b, v0
	v_mul_f32_e32 v0, 0xbfb8aa3b, v0
	v_exp_f32_e32 v0, v0
	s_waitcnt lgkmcnt(12)
	v_lshlrev_b32_e32 v21, 16, v34
	v_exp_f32_e32 v22, v22
	v_cvt_pk_bf16_f32 v20, v20, s0
	v_mul_f32_e32 v0, v0, v21
	ds_write_b16 v59, v20 offset:6336
	v_lshlrev_b32_e32 v20, 16, v26
	v_cvt_pk_bf16_f32 v0, v0, s0
	v_mul_f32_e32 v20, 0x3d800000, v20
	ds_write_b16 v59, v0 offset:40656
	v_add_f32_e32 v0, v92, v19
	v_mul_f32_e32 v20, v22, v20
	v_mul_f32_e32 v22, 0x3fb8aa3b, v0
	v_mul_f32_e32 v0, 0xbfb8aa3b, v0
	v_exp_f32_e32 v0, v0
	s_waitcnt lgkmcnt(13)
	v_lshlrev_b32_e32 v21, 16, v36
	v_exp_f32_e32 v22, v22
	v_cvt_pk_bf16_f32 v20, v20, s0
	v_mul_f32_e32 v0, v0, v21
	ds_write_b16 v59, v20 offset:6864
	v_lshlrev_b32_e32 v20, 16, v27
	v_cvt_pk_bf16_f32 v0, v0, s0
	v_mul_f32_e32 v20, 0x3d800000, v20
	ds_write_b16 v59, v0 offset:41184
	v_add_f32_e32 v0, v94, v19
	v_mul_f32_e32 v20, v22, v20
	v_mul_f32_e32 v37, 0x3fb8aa3b, v0
	v_mul_f32_e32 v0, 0xbfb8aa3b, v0
	v_cvt_pk_bf16_f32 v20, v20, s0
	v_exp_f32_e32 v0, v0
	ds_write_b16 v59, v20 offset:7392
	ds_read_u16 v20, v59 offset:7920
	ds_read_u16 v21, v59 offset:8448
	ds_read_u16 v22, v59 offset:8976
	ds_read_u16 v23, v59 offset:9504
	ds_read_u16 v24, v59 offset:10032
	ds_read_u16 v25, v59 offset:10560
	ds_read_u16 v26, v59 offset:11088
	ds_read_u16 v27, v59 offset:11616
	ds_read_u16 v28, v59 offset:41712
	ds_read_u16 v29, v59 offset:42240
	ds_read_u16 v30, v59 offset:42768
	ds_read_u16 v31, v59 offset:43296
	ds_read_u16 v32, v59 offset:43824
	ds_read_u16 v33, v59 offset:44352
	ds_read_u16 v34, v59 offset:44880
	ds_read_u16 v36, v59 offset:45408
	s_waitcnt lgkmcnt(7)
	v_lshlrev_b32_e32 v28, 16, v28
	v_mul_f32_e32 v0, v0, v28
	v_exp_f32_e32 v37, v37
	v_cvt_pk_bf16_f32 v0, v0, s0
	ds_write_b16 v59, v0 offset:41712
	v_add_f32_e32 v0, v93, v19
	v_lshlrev_b32_e32 v20, 16, v20
	v_mul_f32_e32 v28, 0x3fb8aa3b, v0
	v_mul_f32_e32 v0, 0xbfb8aa3b, v0
	v_mul_f32_e32 v20, 0x3d800000, v20
	v_exp_f32_e32 v0, v0
	v_mul_f32_e32 v20, v37, v20
	v_exp_f32_e32 v28, v28
	v_cvt_pk_bf16_f32 v20, v20, s0
	ds_write_b16 v59, v20 offset:7920
	v_lshlrev_b32_e32 v20, 16, v21
	s_waitcnt lgkmcnt(8)
	v_lshlrev_b32_e32 v21, 16, v29
	v_mul_f32_e32 v20, 0x3d800000, v20
	v_mul_f32_e32 v0, v0, v21
	v_mul_f32_e32 v20, v28, v20
	v_cvt_pk_bf16_f32 v0, v0, s0
	v_cvt_pk_bf16_f32 v20, v20, s0
	ds_write_b16 v59, v0 offset:42240
	v_add_f32_e32 v0, v95, v19
	ds_write_b16 v59, v20 offset:8448
	v_lshlrev_b32_e32 v20, 16, v22
	v_mul_f32_e32 v22, 0x3fb8aa3b, v0
	v_mul_f32_e32 v0, 0xbfb8aa3b, v0
	v_exp_f32_e32 v0, v0
	s_waitcnt lgkmcnt(9)
	v_lshlrev_b32_e32 v21, 16, v30
	v_exp_f32_e32 v22, v22
	v_mul_f32_e32 v20, 0x3d800000, v20
	v_mul_f32_e32 v0, v0, v21
	v_cvt_pk_bf16_f32 v0, v0, s0
	ds_write_b16 v59, v0 offset:42768
	v_add_f32_e32 v0, v96, v19
	v_mul_f32_e32 v20, v22, v20
	v_mul_f32_e32 v22, 0x3fb8aa3b, v0
	v_mul_f32_e32 v0, 0xbfb8aa3b, v0
	v_exp_f32_e32 v0, v0
	s_waitcnt lgkmcnt(9)
	v_lshlrev_b32_e32 v21, 16, v31
	v_exp_f32_e32 v22, v22
	v_cvt_pk_bf16_f32 v20, v20, s0
	v_mul_f32_e32 v0, v0, v21
	ds_write_b16 v59, v20 offset:8976
	v_lshlrev_b32_e32 v20, 16, v23
	v_cvt_pk_bf16_f32 v0, v0, s0
	v_mul_f32_e32 v20, 0x3d800000, v20
	ds_write_b16 v59, v0 offset:43296
	v_add_f32_e32 v0, v98, v19
	v_mul_f32_e32 v20, v22, v20
	v_mul_f32_e32 v22, 0x3fb8aa3b, v0
	v_mul_f32_e32 v0, 0xbfb8aa3b, v0
	v_exp_f32_e32 v0, v0
	s_waitcnt lgkmcnt(10)
	v_lshlrev_b32_e32 v21, 16, v32
	v_exp_f32_e32 v22, v22
	v_cvt_pk_bf16_f32 v20, v20, s0
	v_mul_f32_e32 v0, v0, v21
	ds_write_b16 v59, v20 offset:9504
	v_lshlrev_b32_e32 v20, 16, v24
	v_cvt_pk_bf16_f32 v0, v0, s0
	v_mul_f32_e32 v20, 0x3d800000, v20
	ds_write_b16 v59, v0 offset:43824
	v_add_f32_e32 v0, v97, v19
	v_mul_f32_e32 v20, v22, v20
	v_mul_f32_e32 v22, 0x3fb8aa3b, v0
	v_mul_f32_e32 v0, 0xbfb8aa3b, v0
	v_exp_f32_e32 v0, v0
	s_waitcnt lgkmcnt(11)
	v_lshlrev_b32_e32 v21, 16, v33
	v_exp_f32_e32 v22, v22
	v_cvt_pk_bf16_f32 v20, v20, s0
	v_mul_f32_e32 v0, v0, v21
	ds_write_b16 v59, v20 offset:10032
	v_lshlrev_b32_e32 v20, 16, v25
	v_cvt_pk_bf16_f32 v0, v0, s0
	v_mul_f32_e32 v20, 0x3d800000, v20
	ds_write_b16 v59, v0 offset:44352
	v_add_f32_e32 v0, v99, v19
	v_mul_f32_e32 v20, v22, v20
	v_mul_f32_e32 v22, 0x3fb8aa3b, v0
	v_mul_f32_e32 v0, 0xbfb8aa3b, v0
	v_exp_f32_e32 v0, v0
	s_waitcnt lgkmcnt(12)
	v_lshlrev_b32_e32 v21, 16, v34
	v_exp_f32_e32 v22, v22
	v_cvt_pk_bf16_f32 v20, v20, s0
	v_mul_f32_e32 v0, v0, v21
	ds_write_b16 v59, v20 offset:10560
	v_lshlrev_b32_e32 v20, 16, v26
	v_cvt_pk_bf16_f32 v0, v0, s0
	v_mul_f32_e32 v20, 0x3d800000, v20
	ds_write_b16 v59, v0 offset:44880
	v_add_f32_e32 v0, v100, v19
	v_mul_f32_e32 v20, v22, v20
	v_mul_f32_e32 v22, 0x3fb8aa3b, v0
	v_mul_f32_e32 v0, 0xbfb8aa3b, v0
	v_exp_f32_e32 v0, v0
	s_waitcnt lgkmcnt(13)
	v_lshlrev_b32_e32 v21, 16, v36
	v_exp_f32_e32 v22, v22
	v_cvt_pk_bf16_f32 v20, v20, s0
	v_mul_f32_e32 v0, v0, v21
	ds_write_b16 v59, v20 offset:11088
	v_lshlrev_b32_e32 v20, 16, v27
	v_cvt_pk_bf16_f32 v0, v0, s0
	v_mul_f32_e32 v20, 0x3d800000, v20
	ds_write_b16 v59, v0 offset:45408
	v_add_f32_e32 v0, v102, v19
	v_mul_f32_e32 v20, v22, v20
	v_mul_f32_e32 v37, 0x3fb8aa3b, v0
	v_mul_f32_e32 v0, 0xbfb8aa3b, v0
	v_cvt_pk_bf16_f32 v20, v20, s0
	v_exp_f32_e32 v0, v0
	ds_write_b16 v59, v20 offset:11616
	ds_read_u16 v20, v59 offset:12144
	ds_read_u16 v21, v59 offset:12672
	ds_read_u16 v22, v59 offset:13200
	ds_read_u16 v23, v59 offset:13728
	ds_read_u16 v24, v59 offset:14256
	ds_read_u16 v25, v59 offset:14784
	ds_read_u16 v26, v59 offset:15312
	ds_read_u16 v27, v59 offset:15840
	ds_read_u16 v28, v59 offset:45936
	ds_read_u16 v29, v59 offset:46464
	ds_read_u16 v30, v59 offset:46992
	ds_read_u16 v31, v59 offset:47520
	ds_read_u16 v32, v59 offset:48048
	ds_read_u16 v33, v59 offset:48576
	ds_read_u16 v34, v59 offset:49104
	ds_read_u16 v36, v59 offset:49632
	s_waitcnt lgkmcnt(7)
	v_lshlrev_b32_e32 v28, 16, v28
	v_mul_f32_e32 v0, v0, v28
	v_exp_f32_e32 v37, v37
	v_cvt_pk_bf16_f32 v0, v0, s0
	ds_write_b16 v59, v0 offset:45936
	v_add_f32_e32 v0, v101, v19
	v_lshlrev_b32_e32 v20, 16, v20
	v_mul_f32_e32 v28, 0x3fb8aa3b, v0
	v_mul_f32_e32 v0, 0xbfb8aa3b, v0
	v_mul_f32_e32 v20, 0x3d800000, v20
	v_exp_f32_e32 v0, v0
	v_mul_f32_e32 v20, v37, v20
	v_exp_f32_e32 v28, v28
	v_cvt_pk_bf16_f32 v20, v20, s0
	ds_write_b16 v59, v20 offset:12144
	v_lshlrev_b32_e32 v20, 16, v21
	s_waitcnt lgkmcnt(8)
	v_lshlrev_b32_e32 v21, 16, v29
	v_mul_f32_e32 v20, 0x3d800000, v20
	v_mul_f32_e32 v0, v0, v21
	v_mul_f32_e32 v20, v28, v20
	v_cvt_pk_bf16_f32 v0, v0, s0
	v_cvt_pk_bf16_f32 v20, v20, s0
	ds_write_b16 v59, v0 offset:46464
	v_add_f32_e32 v0, v103, v19
	ds_write_b16 v59, v20 offset:12672
	v_lshlrev_b32_e32 v20, 16, v22
	v_mul_f32_e32 v22, 0x3fb8aa3b, v0
	v_mul_f32_e32 v0, 0xbfb8aa3b, v0
	v_exp_f32_e32 v0, v0
	s_waitcnt lgkmcnt(9)
	v_lshlrev_b32_e32 v21, 16, v30
	v_exp_f32_e32 v22, v22
	v_mul_f32_e32 v20, 0x3d800000, v20
	v_mul_f32_e32 v0, v0, v21
	v_cvt_pk_bf16_f32 v0, v0, s0
	ds_write_b16 v59, v0 offset:46992
	v_add_f32_e32 v0, v104, v19
	v_mul_f32_e32 v20, v22, v20
	v_mul_f32_e32 v22, 0x3fb8aa3b, v0
	v_mul_f32_e32 v0, 0xbfb8aa3b, v0
	v_exp_f32_e32 v0, v0
	s_waitcnt lgkmcnt(9)
	v_lshlrev_b32_e32 v21, 16, v31
	v_exp_f32_e32 v22, v22
	v_cvt_pk_bf16_f32 v20, v20, s0
	v_mul_f32_e32 v0, v0, v21
	ds_write_b16 v59, v20 offset:13200
	v_lshlrev_b32_e32 v20, 16, v23
	v_cvt_pk_bf16_f32 v0, v0, s0
	v_mul_f32_e32 v20, 0x3d800000, v20
	ds_write_b16 v59, v0 offset:47520
	v_add_f32_e32 v0, v107, v19
	v_mul_f32_e32 v20, v22, v20
	v_mul_f32_e32 v22, 0x3fb8aa3b, v0
	v_mul_f32_e32 v0, 0xbfb8aa3b, v0
	v_exp_f32_e32 v0, v0
	s_waitcnt lgkmcnt(10)
	v_lshlrev_b32_e32 v21, 16, v32
	v_exp_f32_e32 v22, v22
	v_cvt_pk_bf16_f32 v20, v20, s0
	v_mul_f32_e32 v0, v0, v21
	ds_write_b16 v59, v20 offset:13728
	v_lshlrev_b32_e32 v20, 16, v24
	v_cvt_pk_bf16_f32 v0, v0, s0
	v_mul_f32_e32 v20, 0x3d800000, v20
	ds_write_b16 v59, v0 offset:48048
	v_add_f32_e32 v0, v106, v19
	v_mul_f32_e32 v20, v22, v20
	v_mul_f32_e32 v22, 0x3fb8aa3b, v0
	v_mul_f32_e32 v0, 0xbfb8aa3b, v0
	v_exp_f32_e32 v0, v0
	s_waitcnt lgkmcnt(11)
	v_lshlrev_b32_e32 v21, 16, v33
	v_exp_f32_e32 v22, v22
	v_cvt_pk_bf16_f32 v20, v20, s0
	v_mul_f32_e32 v0, v0, v21
	ds_write_b16 v59, v20 offset:14256
	v_lshlrev_b32_e32 v20, 16, v25
	v_cvt_pk_bf16_f32 v0, v0, s0
	v_mul_f32_e32 v20, 0x3d800000, v20
	ds_write_b16 v59, v0 offset:48576
	v_add_f32_e32 v0, v105, v19
	v_mul_f32_e32 v20, v22, v20
	v_mul_f32_e32 v22, 0x3fb8aa3b, v0
	v_mul_f32_e32 v0, 0xbfb8aa3b, v0
	v_exp_f32_e32 v0, v0
	s_waitcnt lgkmcnt(12)
	v_lshlrev_b32_e32 v21, 16, v34
	v_exp_f32_e32 v22, v22
	v_cvt_pk_bf16_f32 v20, v20, s0
	v_mul_f32_e32 v0, v0, v21
	ds_write_b16 v59, v20 offset:14784
	v_lshlrev_b32_e32 v20, 16, v26
	v_cvt_pk_bf16_f32 v0, v0, s0
	v_mul_f32_e32 v20, 0x3d800000, v20
	ds_write_b16 v59, v0 offset:49104
	v_add_f32_e32 v0, v109, v19
	v_mul_f32_e32 v20, v22, v20
	v_mul_f32_e32 v22, 0x3fb8aa3b, v0
	v_exp_f32_e32 v22, v22
	v_mul_f32_e32 v0, 0xbfb8aa3b, v0
	v_cvt_pk_bf16_f32 v20, v20, s0
	v_exp_f32_e32 v0, v0
	ds_write_b16 v59, v20 offset:15312
	v_lshlrev_b32_e32 v20, 16, v27
	v_mul_f32_e32 v20, 0x3d800000, v20
	s_waitcnt lgkmcnt(14)
	v_lshlrev_b32_e32 v21, 16, v36
	v_mul_f32_e32 v20, v22, v20
	v_cvt_pk_bf16_f32 v20, v20, s0
	v_mul_f32_e32 v0, v0, v21
	ds_write_b16 v59, v20 offset:15840
	ds_read_u16 v20, v59 offset:16368
	v_cvt_pk_bf16_f32 v0, v0, s0
	ds_write_b16 v59, v0 offset:49632
	v_add_f32_e32 v0, v19, v108
	v_mul_f32_e32 v21, 0x3fb8aa3b, v0
	v_mul_f32_e32 v0, 0xbfb8aa3b, v0
	v_exp_f32_e32 v21, v21
	v_exp_f32_e32 v0, v0
	s_waitcnt lgkmcnt(1)
	v_lshlrev_b32_e32 v19, 16, v20
	v_lshlrev_b32_e32 v20, 16, v35
	v_mul_f32_e32 v19, 0x3d800000, v19
	v_mul_f32_e32 v19, v21, v19
	v_mul_f32_e32 v0, v0, v20
	v_cvt_pk_bf16_f32 v19, v19, s0
	v_cvt_pk_bf16_f32 v0, v0, s0
	ds_write_b16 v59, v19 offset:16368
	ds_write_b16 v59, v0 offset:50160
	s_and_saveexec_b64 s[64:65], s[4:5]
	s_cbranch_execz .LBB0_613
	ds_read_b32 v0, v57 offset:1024
	s_ashr_i32 s37, s36, 31
	s_lshl_b64 s[66:67], s[36:37], 10
	s_waitcnt lgkmcnt(0)
	v_add_f32_e32 v0, v18, v0
	v_mul_f32_e32 v0, 0x3fb8aa3b, v0
	v_exp_f32_e32 v0, v0
	v_lshl_add_u64 v[18:19], v[62:63], 0, s[66:67]
	ds_write_b32 v51, v0
	global_store_dword v[18:19], v0, off
